# Wo epilogue: nt cache hint on the once-read f32 residual prefetch loads
# speedup vs baseline: 1.0109x; 1.0109x over previous
; __device__ __forceinline__ unsigned cvt_pk_bf16(float lo, float hi) { unsigned r; asm volatile("v_cvt_pk_bf16_f32 %0, %1, %2" : "=v"(r) : "v"(lo), "v"(hi)); return r; }
;     __device__ __forceinline__ void operator()(const f32x4 (&acc)[2][2][4][2], const Unit& u, int wr, int wc, int fr, int fq) const {
;         const int row0 = u.pm * BM + wr * 64 + fr, col0 = u.pn * BM + wc * 32 + 4 * fq;
; #pragma unroll
;         for (int ai = 0; ai < 2; ++ai)
; #pragma unroll
;             for (int m = 0; m < 4; ++m) { const int lrow = row0 + ai * HALF + m * 16; const int grow = grow0 + lrow;
;                 const float* xr = (grow < 65536) ? xp + (size_t)grow * 1024 : xs + (size_t)(grow - 65536) * 1024;
;                 bf16_t* brow = XB + (size_t)lrow * 1024; float ss = 0.f;
; #pragma unroll
;                 for (int bj = 0; bj < 2; ++bj)
; #pragma unroll
;                     for (int n = 0; n < 2; ++n) { const int c = col0 + bj * HALF + n * 16; const f32x4 xv = *(const f32x4*)(xr + c); const f32x4 o = xv + acc[ai][bj][m][n];
;                         ss += (o[0] * o[0] + o[1] * o[1]) + (o[2] * o[2] + o[3] * o[3]);
;                         u32x2 w; w.x = cvt_pk_bf16(o[0], o[1]); w.y = cvt_pk_bf16(o[2], o[3]); *(u32x2*)(brow + c) = w; }
;                 ss += __shfl_xor(ss, 16); ss += __shfl_xor(ss, 32);
;                 if (fq == 0) atomicAdd(SS + grow, ss); }
.LBB0_773:
	v_lshl_add_u32 v144, s64, 8, v1
	v_add_u32_e32 v146, s40, v144
	s_mov_b32 s25, 0x10000
	v_add_u32_e32 v143, 0xffff0000, v146
	v_cmp_gt_i32_e32 vcc, s25, v146
	v_ashrrev_i32_e32 v147, 31, v146
	v_mov_b32_e32 v145, s9
	v_cndmask_b32_e32 v152, v143, v146, vcc
	v_mov_b32_e32 v143, s11
	v_cndmask_b32_e32 v153, 0, v147, vcc
	v_cndmask_b32_e32 v155, v143, v145, vcc
	v_mov_b32_e32 v143, s10
	v_mov_b32_e32 v145, s8
	v_lshl_or_b32 v142, s62, 8, v149
	v_cndmask_b32_e32 v154, v143, v145, vcc
	v_lshlrev_b64 v[152:153], 12, v[152:153]
	v_lshl_add_u64 v[152:153], v[154:155], 0, v[152:153]
	v_ashrrev_i32_e32 v143, 31, v142
	v_lshl_add_u64 v[156:157], v[142:143], 2, v[152:153]
	v_mov_b32_e32 v252, v156
	v_mov_b32_e32 v253, v157
	s_mov_b32 s77, 0
	global_load_dwordx4 v[200:203], v[252:253], off nt
	global_load_dwordx4 v[204:207], v[252:253], off offset:64 nt
	global_load_dwordx4 v[208:211], v[252:253], off offset:512 nt
	global_load_dwordx4 v[212:215], v[252:253], off offset:576 nt
	s_mov_b32 s76, 0x10000
	v_lshl_add_u64 v[250:251], v[252:253], 0, s[76:77]
	global_load_dwordx4 v[216:219], v[250:251], off nt
	global_load_dwordx4 v[220:223], v[250:251], off offset:64 nt
	global_load_dwordx4 v[224:227], v[250:251], off offset:512 nt
	global_load_dwordx4 v[228:231], v[250:251], off offset:576 nt
	s_mov_b32 s76, 0x20000
	v_lshl_add_u64 v[250:251], v[252:253], 0, s[76:77]
	global_load_dwordx4 v[232:235], v[250:251], off nt
	global_load_dwordx4 v[236:239], v[250:251], off offset:64 nt
	global_load_dwordx4 v[240:243], v[250:251], off offset:512 nt
	global_load_dwordx4 v[244:247], v[250:251], off offset:576 nt
	v_ashrrev_i32_e32 v145, 31, v144
	v_lshlrev_b64 v[158:159], 11, v[144:145]
	v_lshl_add_u64 v[158:159], s[14:15], 0, v[158:159]
	v_lshl_add_u64 v[158:159], v[142:143], 1, v[158:159]
	s_waitcnt vmcnt(11)
	v_mov_b32_e32 v152, v200
	v_mov_b32_e32 v153, v201
	v_mov_b32_e32 v154, v202
	v_mov_b32_e32 v155, v203
	v_pk_add_f32 v[154:155], v[132:133], v[154:155]
	v_pk_add_f32 v[152:153], v[130:131], v[152:153]
	v_mul_f32_e32 v151, v155, v155
	v_cvt_pk_bf16_f32 v130, v152, v153
	v_cvt_pk_bf16_f32 v131, v154, v155
	global_store_dwordx2 v[158:159], v[130:131], off
	v_mul_f32_e32 v145, v153, v153
	v_fmac_f32_e32 v145, v152, v152
	v_fmac_f32_e32 v151, v154, v154
	v_add_f32_e32 v145, v145, v151
	s_waitcnt vmcnt(11)
	v_mov_b32_e32 v130, v204
	v_mov_b32_e32 v131, v205
	v_mov_b32_e32 v132, v206
	v_mov_b32_e32 v133, v207
	v_pk_add_f32 v[132:133], v[128:129], v[132:133]
	v_pk_add_f32 v[130:131], v[126:127], v[130:131]
	s_nop 0
	v_cvt_pk_bf16_f32 v126, v130, v131
	v_cvt_pk_bf16_f32 v127, v132, v133
	global_store_dwordx2 v[158:159], v[126:127], off offset:32
	v_mul_f32_e32 v131, v131, v131
	v_mul_f32_e32 v133, v133, v133
	v_fmac_f32_e32 v131, v130, v130
	v_fmac_f32_e32 v133, v132, v132
	v_add_f32_e32 v130, v131, v133
	v_add_f32_e32 v130, v145, v130
	s_waitcnt vmcnt(11)
	v_mov_b32_e32 v126, v208
	v_mov_b32_e32 v127, v209
	v_mov_b32_e32 v128, v210
	v_mov_b32_e32 v129, v211
	v_pk_add_f32 v[128:129], v[124:125], v[128:129]
	v_pk_add_f32 v[160:161], v[122:123], v[126:127]
	s_nop 0
	v_cvt_pk_bf16_f32 v122, v160, v161
	v_cvt_pk_bf16_f32 v123, v128, v129
	global_store_dwordx2 v[158:159], v[122:123], off offset:256
	v_and_b32_e32 v123, 64, v194
	v_mul_f32_e32 v131, v161, v161
	v_mul_f32_e32 v129, v129, v129
	v_xor_b32_e32 v122, 16, v194
	v_add_u32_e32 v123, 64, v123
	v_fmac_f32_e32 v131, v160, v160
	v_fmac_f32_e32 v129, v128, v128
	v_cmp_lt_i32_e32 vcc, v122, v123
	v_add_f32_e32 v128, v131, v129
	v_add_f32_e32 v128, v130, v128
	v_cndmask_b32_e32 v122, v194, v122, vcc
	v_lshlrev_b32_e32 v122, 2, v122
	s_waitcnt vmcnt(11)
	v_mov_b32_e32 v124, v212
	v_mov_b32_e32 v125, v213
	v_mov_b32_e32 v126, v214
	v_mov_b32_e32 v127, v215
	s_mov_b32 s76, 0x30000
	v_lshl_add_u64 v[250:251], v[252:253], 0, s[76:77]
	global_load_dwordx4 v[200:203], v[250:251], off nt
	global_load_dwordx4 v[204:207], v[250:251], off offset:64 nt
	global_load_dwordx4 v[208:211], v[250:251], off offset:512 nt
	global_load_dwordx4 v[212:215], v[250:251], off offset:576 nt
	v_pk_add_f32 v[126:127], v[120:121], v[126:127]
	v_pk_add_f32 v[124:125], v[118:119], v[124:125]
	v_mul_f32_e32 v119, v127, v127
	v_mul_f32_e32 v118, v125, v125
	v_fmac_f32_e32 v118, v124, v124
	v_fmac_f32_e32 v119, v126, v126
	v_add_f32_e32 v118, v118, v119
	v_add_f32_e32 v118, v128, v118
	ds_bpermute_b32 v119, v122, v118
	v_xor_b32_e32 v120, 32, v194
	v_cmp_lt_i32_e32 vcc, v120, v123
	v_cvt_pk_bf16_f32 v124, v124, v125
	v_cvt_pk_bf16_f32 v125, v126, v127
	s_waitcnt lgkmcnt(0)
	v_add_f32_e32 v118, v118, v119
	global_store_dwordx2 v[158:159], v[124:125], off offset:288
	v_cndmask_b32_e32 v120, v194, v120, vcc
	v_lshlrev_b32_e32 v120, 2, v120
	ds_bpermute_b32 v119, v120, v118
	s_and_saveexec_b64 s[62:63], s[4:5]
	s_cbranch_execz .LBB0_775
	s_waitcnt lgkmcnt(0)
	v_add_f32_e32 v121, v118, v119
	v_lshl_add_u64 v[118:119], v[146:147], 2, s[18:19]
	global_atomic_add_f32 v[118:119], v121, off
; __device__ __forceinline__ unsigned cvt_pk_bf16(float lo, float hi) { unsigned r; asm volatile("v_cvt_pk_bf16_f32 %0, %1, %2" : "=v"(r) : "v"(lo), "v"(hi)); return r; }
;     __device__ __forceinline__ void operator()(const f32x4 (&acc)[2][2][4][2], const Unit& u, int wr, int wc, int fr, int fq) const {
;     ...
;             for (int m = 0; m < 4; ++m) { const int lrow = row0 + ai * HALF + m * 16; const int grow = grow0 + lrow;
;                 const float* xr = (grow < 65536) ? xp + (size_t)grow * 1024 : xs + (size_t)(grow - 65536) * 1024;
;                 bf16_t* brow = XB + (size_t)lrow * 1024; float ss = 0.f;
; #pragma unroll
;                 for (int bj = 0; bj < 2; ++bj)
; #pragma unroll
;                     for (int n = 0; n < 2; ++n) { const int c = col0 + bj * HALF + n * 16; const f32x4 xv = *(const f32x4*)(xr + c); const f32x4 o = xv + acc[ai][bj][m][n];
;                         ss += (o[0] * o[0] + o[1] * o[1]) + (o[2] * o[2] + o[3] * o[3]);
;                         u32x2 w; w.x = cvt_pk_bf16(o[0], o[1]); w.y = cvt_pk_bf16(o[2], o[3]); *(u32x2*)(brow + c) = w; }
;                 ss += __shfl_xor(ss, 16); ss += __shfl_xor(ss, 32);
;                 if (fq == 0) atomicAdd(SS + grow, ss); }
.LBB0_775:
	s_or_b64 exec, exec, s[62:63]
	v_or_b32_e32 v128, 16, v144
	v_add_u32_e32 v118, s40, v128
	v_add_u32_e32 v121, 0xffff0000, v118
	v_cmp_gt_i32_e32 vcc, s25, v118
	s_waitcnt lgkmcnt(0)
	v_ashrrev_i32_e32 v119, 31, v118
	v_mov_b32_e32 v123, s9
	v_cndmask_b32_e32 v124, v121, v118, vcc
	v_mov_b32_e32 v121, s11
	v_cndmask_b32_e32 v125, 0, v119, vcc
	v_cndmask_b32_e32 v127, v121, v123, vcc
	v_mov_b32_e32 v121, s10
	v_mov_b32_e32 v123, s8
	v_cndmask_b32_e32 v126, v121, v123, vcc
	v_lshlrev_b64 v[124:125], 12, v[124:125]
	v_lshl_add_u64 v[124:125], v[126:127], 0, v[124:125]
	v_lshl_add_u64 v[130:131], v[142:143], 2, v[124:125]
	v_ashrrev_i32_e32 v129, 31, v128
	v_lshlrev_b64 v[128:129], 11, v[128:129]
	v_lshl_add_u64 v[128:129], s[14:15], 0, v[128:129]
	v_lshl_add_u64 v[128:129], v[142:143], 1, v[128:129]
	s_waitcnt vmcnt(16)
	v_mov_b32_e32 v124, v216
	v_mov_b32_e32 v125, v217
	v_mov_b32_e32 v126, v218
	v_mov_b32_e32 v127, v219
	v_pk_add_f32 v[126:127], v[116:117], v[126:127]
	v_pk_add_f32 v[124:125], v[114:115], v[124:125]
	v_mul_f32_e32 v123, v127, v127
	v_cvt_pk_bf16_f32 v114, v124, v125
	v_cvt_pk_bf16_f32 v115, v126, v127
	global_store_dwordx2 v[128:129], v[114:115], off
	v_mul_f32_e32 v121, v125, v125
	v_fmac_f32_e32 v121, v124, v124
	v_fmac_f32_e32 v123, v126, v126
	v_add_f32_e32 v121, v121, v123
	s_waitcnt vmcnt(16)
	v_mov_b32_e32 v114, v220
	v_mov_b32_e32 v115, v221
	v_mov_b32_e32 v116, v222
	v_mov_b32_e32 v117, v223
	v_pk_add_f32 v[116:117], v[112:113], v[116:117]
	v_pk_add_f32 v[114:115], v[110:111], v[114:115]
	s_nop 0
	v_cvt_pk_bf16_f32 v110, v114, v115
	v_cvt_pk_bf16_f32 v111, v116, v117
	global_store_dwordx2 v[128:129], v[110:111], off offset:32
	v_mul_f32_e32 v115, v115, v115
	v_mul_f32_e32 v117, v117, v117
	v_fmac_f32_e32 v115, v114, v114
	v_fmac_f32_e32 v117, v116, v116
	v_add_f32_e32 v114, v115, v117
	v_add_f32_e32 v114, v121, v114
	s_waitcnt vmcnt(16)
	v_mov_b32_e32 v110, v224
	v_mov_b32_e32 v111, v225
	v_mov_b32_e32 v112, v226
	v_mov_b32_e32 v113, v227
	v_pk_add_f32 v[112:113], v[108:109], v[112:113]
	v_pk_add_f32 v[110:111], v[106:107], v[110:111]
	s_nop 0
	v_cvt_pk_bf16_f32 v106, v110, v111
	v_cvt_pk_bf16_f32 v107, v112, v113
	global_store_dwordx2 v[128:129], v[106:107], off offset:256
	v_mul_f32_e32 v111, v111, v111
	v_mul_f32_e32 v113, v113, v113
	v_fmac_f32_e32 v111, v110, v110
	v_fmac_f32_e32 v113, v112, v112
	v_add_f32_e32 v110, v111, v113
	v_add_f32_e32 v110, v114, v110
	s_waitcnt vmcnt(16)
	v_mov_b32_e32 v106, v228
	v_mov_b32_e32 v107, v229
	v_mov_b32_e32 v108, v230
	v_mov_b32_e32 v109, v231
	s_mov_b32 s76, 0x80000
	v_lshl_add_u64 v[250:251], v[252:253], 0, s[76:77]
	global_load_dwordx4 v[216:219], v[250:251], off nt
	global_load_dwordx4 v[220:223], v[250:251], off offset:64 nt
	global_load_dwordx4 v[224:227], v[250:251], off offset:512 nt
	global_load_dwordx4 v[228:231], v[250:251], off offset:576 nt
	v_pk_add_f32 v[104:105], v[104:105], v[108:109]
	v_pk_add_f32 v[106:107], v[102:103], v[106:107]
	v_mul_f32_e32 v103, v105, v105
	v_mul_f32_e32 v102, v107, v107
	v_fmac_f32_e32 v102, v106, v106
	v_fmac_f32_e32 v103, v104, v104
	v_add_f32_e32 v102, v102, v103
	v_add_f32_e32 v102, v110, v102
	ds_bpermute_b32 v103, v122, v102
	v_cvt_pk_bf16_f32 v106, v106, v107
	v_cvt_pk_bf16_f32 v107, v104, v105
	global_store_dwordx2 v[128:129], v[106:107], off offset:288
	s_waitcnt lgkmcnt(0)
	v_add_f32_e32 v102, v102, v103
	ds_bpermute_b32 v103, v120, v102
	s_and_saveexec_b64 s[62:63], s[4:5]
	s_cbranch_execz .LBB0_777
	s_waitcnt lgkmcnt(0)
	v_add_f32_e32 v104, v102, v103
	v_lshl_add_u64 v[102:103], v[118:119], 2, s[18:19]
	global_atomic_add_f32 v[102:103], v104, off
.LBB0_777:
	s_or_b64 exec, exec, s[62:63]
	v_or_b32_e32 v108, 32, v144
	v_add_u32_e32 v102, s40, v108
	s_waitcnt lgkmcnt(0)
	v_ashrrev_i32_e32 v103, 31, v102
	v_add_u32_e32 v104, 0xffff0000, v102
	v_cmp_gt_i32_e32 vcc, s25, v102
	v_mov_b32_e32 v106, s11
	v_mov_b32_e32 v107, s9
	v_cndmask_b32_e32 v105, 0, v103, vcc
	v_cndmask_b32_e32 v104, v104, v102, vcc
	v_cndmask_b32_e32 v107, v106, v107, vcc
	v_mov_b32_e32 v106, s10
	v_mov_b32_e32 v109, s8
	v_cndmask_b32_e32 v106, v106, v109, vcc
	v_lshlrev_b64 v[104:105], 12, v[104:105]
	v_lshl_add_u64 v[104:105], v[106:107], 0, v[104:105]
	v_lshl_add_u64 v[110:111], v[142:143], 2, v[104:105]
	v_ashrrev_i32_e32 v109, 31, v108
	v_lshlrev_b64 v[108:109], 11, v[108:109]
	v_lshl_add_u64 v[108:109], s[14:15], 0, v[108:109]
	v_lshl_add_u64 v[108:109], v[142:143], 1, v[108:109]
	s_waitcnt vmcnt(21)
	v_mov_b32_e32 v104, v232
	v_mov_b32_e32 v105, v233
	v_mov_b32_e32 v106, v234
	v_mov_b32_e32 v107, v235
	v_pk_add_f32 v[106:107], v[100:101], v[106:107]
	v_pk_add_f32 v[104:105], v[98:99], v[104:105]
	s_nop 0
	v_cvt_pk_bf16_f32 v98, v104, v105
	v_cvt_pk_bf16_f32 v99, v106, v107
	global_store_dwordx2 v[108:109], v[98:99], off
	v_mul_f32_e32 v105, v105, v105
	v_mul_f32_e32 v107, v107, v107
	v_fmac_f32_e32 v105, v104, v104
	v_fmac_f32_e32 v107, v106, v106
	v_add_f32_e32 v104, v105, v107
	s_waitcnt vmcnt(21)
	v_mov_b32_e32 v98, v236
	v_mov_b32_e32 v99, v237
	v_mov_b32_e32 v100, v238
	v_mov_b32_e32 v101, v239
	v_pk_add_f32 v[100:101], v[96:97], v[100:101]
	v_pk_add_f32 v[98:99], v[94:95], v[98:99]
	s_nop 0
	v_cvt_pk_bf16_f32 v94, v98, v99
	v_cvt_pk_bf16_f32 v95, v100, v101
	global_store_dwordx2 v[108:109], v[94:95], off offset:32
	v_mul_f32_e32 v99, v99, v99
	v_mul_f32_e32 v101, v101, v101
	v_fmac_f32_e32 v99, v98, v98
	v_fmac_f32_e32 v101, v100, v100
	v_add_f32_e32 v98, v99, v101
	v_add_f32_e32 v98, v104, v98
	s_waitcnt vmcnt(21)
	v_mov_b32_e32 v94, v240
	v_mov_b32_e32 v95, v241
	v_mov_b32_e32 v96, v242
	v_mov_b32_e32 v97, v243
	v_pk_add_f32 v[96:97], v[92:93], v[96:97]
	v_pk_add_f32 v[94:95], v[90:91], v[94:95]
	s_nop 0
	v_cvt_pk_bf16_f32 v90, v94, v95
	v_cvt_pk_bf16_f32 v91, v96, v97
	global_store_dwordx2 v[108:109], v[90:91], off offset:256
	v_mul_f32_e32 v95, v95, v95
	v_mul_f32_e32 v97, v97, v97
	v_fmac_f32_e32 v95, v94, v94
	v_fmac_f32_e32 v97, v96, v96
	v_add_f32_e32 v94, v95, v97
	v_add_f32_e32 v94, v98, v94
	s_waitcnt vmcnt(21)
	v_mov_b32_e32 v90, v244
	v_mov_b32_e32 v91, v245
	v_mov_b32_e32 v92, v246
	v_mov_b32_e32 v93, v247
	s_mov_b32 s76, 0x90000
	v_lshl_add_u64 v[250:251], v[252:253], 0, s[76:77]
	global_load_dwordx4 v[232:235], v[250:251], off nt
	global_load_dwordx4 v[236:239], v[250:251], off offset:64 nt
	global_load_dwordx4 v[240:243], v[250:251], off offset:512 nt
	global_load_dwordx4 v[244:247], v[250:251], off offset:576 nt
	v_pk_add_f32 v[88:89], v[88:89], v[92:93]
	v_pk_add_f32 v[90:91], v[86:87], v[90:91]
	v_mul_f32_e32 v87, v89, v89
	v_mul_f32_e32 v86, v91, v91
	v_fmac_f32_e32 v86, v90, v90
	v_fmac_f32_e32 v87, v88, v88
	v_add_f32_e32 v86, v86, v87
	v_add_f32_e32 v86, v94, v86
	ds_bpermute_b32 v87, v122, v86
	v_cvt_pk_bf16_f32 v90, v90, v91
	v_cvt_pk_bf16_f32 v91, v88, v89
	global_store_dwordx2 v[108:109], v[90:91], off offset:288
	s_waitcnt lgkmcnt(0)
	v_add_f32_e32 v86, v86, v87
	ds_bpermute_b32 v87, v120, v86
	s_and_saveexec_b64 s[62:63], s[4:5]
	s_cbranch_execz .LBB0_779
; __device__ __forceinline__ unsigned cvt_pk_bf16(float lo, float hi) { unsigned r; asm volatile("v_cvt_pk_bf16_f32 %0, %1, %2" : "=v"(r) : "v"(lo), "v"(hi)); return r; }
;     __device__ __forceinline__ void operator()(const f32x4 (&acc)[2][2][4][2], const Unit& u, int wr, int wc, int fr, int fq) const {
;     ...
;             for (int m = 0; m < 4; ++m) { const int lrow = row0 + ai * HALF + m * 16; const int grow = grow0 + lrow;
;                 const float* xr = (grow < 65536) ? xp + (size_t)grow * 1024 : xs + (size_t)(grow - 65536) * 1024;
;                 bf16_t* brow = XB + (size_t)lrow * 1024; float ss = 0.f;
; #pragma unroll
;                 for (int bj = 0; bj < 2; ++bj)
; #pragma unroll
;                     for (int n = 0; n < 2; ++n) { const int c = col0 + bj * HALF + n * 16; const f32x4 xv = *(const f32x4*)(xr + c); const f32x4 o = xv + acc[ai][bj][m][n];
;                         ss += (o[0] * o[0] + o[1] * o[1]) + (o[2] * o[2] + o[3] * o[3]);
;                         u32x2 w; w.x = cvt_pk_bf16(o[0], o[1]); w.y = cvt_pk_bf16(o[2], o[3]); *(u32x2*)(brow + c) = w; }
;                 ss += __shfl_xor(ss, 16); ss += __shfl_xor(ss, 32);
;                 if (fq == 0) atomicAdd(SS + grow, ss); }
	s_waitcnt lgkmcnt(0)
	v_add_f32_e32 v88, v86, v87
	v_lshl_add_u64 v[86:87], v[102:103], 2, s[18:19]
	global_atomic_add_f32 v[86:87], v88, off
.LBB0_779:
	s_or_b64 exec, exec, s[62:63]
	v_or_b32_e32 v92, 48, v144
	v_add_u32_e32 v86, s40, v92
	s_waitcnt lgkmcnt(0)
	v_ashrrev_i32_e32 v87, 31, v86
	v_add_u32_e32 v88, 0xffff0000, v86
	v_cmp_gt_i32_e32 vcc, s25, v86
	v_mov_b32_e32 v90, s11
	v_mov_b32_e32 v91, s9
	v_cndmask_b32_e32 v89, 0, v87, vcc
	v_cndmask_b32_e32 v88, v88, v86, vcc
	v_cndmask_b32_e32 v91, v90, v91, vcc
	v_mov_b32_e32 v90, s10
	v_mov_b32_e32 v93, s8
	v_cndmask_b32_e32 v90, v90, v93, vcc
	v_lshlrev_b64 v[88:89], 12, v[88:89]
	v_lshl_add_u64 v[88:89], v[90:91], 0, v[88:89]
	v_lshl_add_u64 v[94:95], v[142:143], 2, v[88:89]
	v_ashrrev_i32_e32 v93, 31, v92
	v_lshlrev_b64 v[92:93], 11, v[92:93]
	v_lshl_add_u64 v[92:93], s[14:15], 0, v[92:93]
	v_lshl_add_u64 v[92:93], v[142:143], 1, v[92:93]
	s_waitcnt vmcnt(23)
	v_mov_b32_e32 v88, v200
	v_mov_b32_e32 v89, v201
	v_mov_b32_e32 v90, v202
	v_mov_b32_e32 v91, v203
	v_pk_add_f32 v[90:91], v[80:81], v[90:91]
	v_pk_add_f32 v[88:89], v[78:79], v[88:89]
	s_nop 0
	v_cvt_pk_bf16_f32 v78, v88, v89
	v_cvt_pk_bf16_f32 v79, v90, v91
	global_store_dwordx2 v[92:93], v[78:79], off
	v_mul_f32_e32 v89, v89, v89
	v_mul_f32_e32 v91, v91, v91
	v_fmac_f32_e32 v89, v88, v88
	v_fmac_f32_e32 v91, v90, v90
	v_add_f32_e32 v88, v89, v91
	s_waitcnt vmcnt(23)
	v_mov_b32_e32 v78, v204
	v_mov_b32_e32 v79, v205
	v_mov_b32_e32 v80, v206
	v_mov_b32_e32 v81, v207
	v_pk_add_f32 v[80:81], v[76:77], v[80:81]
	v_pk_add_f32 v[78:79], v[74:75], v[78:79]
	s_nop 0
	v_cvt_pk_bf16_f32 v74, v78, v79
	v_cvt_pk_bf16_f32 v75, v80, v81
	global_store_dwordx2 v[92:93], v[74:75], off offset:32
	v_mul_f32_e32 v79, v79, v79
	v_mul_f32_e32 v81, v81, v81
	v_fmac_f32_e32 v79, v78, v78
	v_fmac_f32_e32 v81, v80, v80
	v_add_f32_e32 v78, v79, v81
	v_add_f32_e32 v78, v88, v78
	s_waitcnt vmcnt(23)
	v_mov_b32_e32 v74, v208
	v_mov_b32_e32 v75, v209
	v_mov_b32_e32 v76, v210
	v_mov_b32_e32 v77, v211
	v_pk_add_f32 v[76:77], v[72:73], v[76:77]
	v_pk_add_f32 v[74:75], v[70:71], v[74:75]
	s_nop 0
	v_cvt_pk_bf16_f32 v70, v74, v75
	v_cvt_pk_bf16_f32 v71, v76, v77
	global_store_dwordx2 v[92:93], v[70:71], off offset:256
	v_mul_f32_e32 v75, v75, v75
	v_mul_f32_e32 v77, v77, v77
	v_fmac_f32_e32 v75, v74, v74
	v_fmac_f32_e32 v77, v76, v76
	v_add_f32_e32 v74, v75, v77
	v_add_f32_e32 v74, v78, v74
	s_waitcnt vmcnt(23)
	v_mov_b32_e32 v70, v212
	v_mov_b32_e32 v71, v213
	v_mov_b32_e32 v72, v214
	v_mov_b32_e32 v73, v215
	s_mov_b32 s76, 0xa0000
	v_lshl_add_u64 v[250:251], v[252:253], 0, s[76:77]
	global_load_dwordx4 v[200:203], v[250:251], off nt
	global_load_dwordx4 v[204:207], v[250:251], off offset:64 nt
	global_load_dwordx4 v[208:211], v[250:251], off offset:512 nt
	global_load_dwordx4 v[212:215], v[250:251], off offset:576 nt
	v_pk_add_f32 v[68:69], v[68:69], v[72:73]
	v_pk_add_f32 v[70:71], v[66:67], v[70:71]
	v_mul_f32_e32 v67, v69, v69
	v_mul_f32_e32 v66, v71, v71
	v_fmac_f32_e32 v66, v70, v70
	v_fmac_f32_e32 v67, v68, v68
	v_add_f32_e32 v66, v66, v67
	v_add_f32_e32 v66, v74, v66
	ds_bpermute_b32 v67, v122, v66
	v_cvt_pk_bf16_f32 v70, v70, v71
	v_cvt_pk_bf16_f32 v71, v68, v69
	global_store_dwordx2 v[92:93], v[70:71], off offset:288
	s_waitcnt lgkmcnt(0)
	v_add_f32_e32 v66, v66, v67
	ds_bpermute_b32 v67, v120, v66
	s_and_saveexec_b64 s[62:63], s[4:5]
	s_cbranch_execz .LBB0_781
	s_waitcnt lgkmcnt(0)
	v_add_f32_e32 v68, v66, v67
	v_lshl_add_u64 v[66:67], v[86:87], 2, s[18:19]
	global_atomic_add_f32 v[66:67], v68, off
.LBB0_781:
	s_or_b64 exec, exec, s[62:63]
	v_add_u32_e32 v72, 0x80, v144
	v_add_u32_e32 v66, s40, v72
	s_waitcnt lgkmcnt(0)
	v_ashrrev_i32_e32 v67, 31, v66
	v_add_u32_e32 v68, 0xffff0000, v66
	v_cmp_gt_i32_e32 vcc, s25, v66
	v_mov_b32_e32 v70, s11
	v_mov_b32_e32 v71, s9
	v_cndmask_b32_e32 v69, 0, v67, vcc
	v_cndmask_b32_e32 v68, v68, v66, vcc
	v_cndmask_b32_e32 v71, v70, v71, vcc
	v_mov_b32_e32 v70, s10
	v_mov_b32_e32 v73, s8
	v_cndmask_b32_e32 v70, v70, v73, vcc
	v_lshlrev_b64 v[68:69], 12, v[68:69]
	v_lshl_add_u64 v[68:69], v[70:71], 0, v[68:69]
	v_lshl_add_u64 v[74:75], v[142:143], 2, v[68:69]
	v_ashrrev_i32_e32 v73, 31, v72
	v_lshlrev_b64 v[72:73], 11, v[72:73]
	v_lshl_add_u64 v[72:73], s[14:15], 0, v[72:73]
	v_lshl_add_u64 v[72:73], v[142:143], 1, v[72:73]
	s_waitcnt vmcnt(23)
	v_mov_b32_e32 v68, v216
	v_mov_b32_e32 v69, v217
	v_mov_b32_e32 v70, v218
	v_mov_b32_e32 v71, v219
	v_pk_add_f32 v[70:71], v[64:65], v[70:71]
	v_pk_add_f32 v[68:69], v[62:63], v[68:69]
	s_nop 0
	v_cvt_pk_bf16_f32 v62, v68, v69
	v_cvt_pk_bf16_f32 v63, v70, v71
	global_store_dwordx2 v[72:73], v[62:63], off
	v_mul_f32_e32 v69, v69, v69
	v_mul_f32_e32 v71, v71, v71
	v_fmac_f32_e32 v69, v68, v68
	v_fmac_f32_e32 v71, v70, v70
	v_add_f32_e32 v68, v69, v71
	s_waitcnt vmcnt(23)
	v_mov_b32_e32 v62, v220
	v_mov_b32_e32 v63, v221
	v_mov_b32_e32 v64, v222
	v_mov_b32_e32 v65, v223
	v_pk_add_f32 v[64:65], v[60:61], v[64:65]
	v_pk_add_f32 v[62:63], v[58:59], v[62:63]
	s_nop 0
	v_cvt_pk_bf16_f32 v58, v62, v63
	v_cvt_pk_bf16_f32 v59, v64, v65
	global_store_dwordx2 v[72:73], v[58:59], off offset:32
	v_mul_f32_e32 v63, v63, v63
	v_mul_f32_e32 v65, v65, v65
	v_fmac_f32_e32 v63, v62, v62
	v_fmac_f32_e32 v65, v64, v64
	v_add_f32_e32 v62, v63, v65
	v_add_f32_e32 v62, v68, v62
	s_waitcnt vmcnt(23)
	v_mov_b32_e32 v58, v224
	v_mov_b32_e32 v59, v225
	v_mov_b32_e32 v60, v226
	v_mov_b32_e32 v61, v227
	v_pk_add_f32 v[60:61], v[56:57], v[60:61]
	v_pk_add_f32 v[58:59], v[54:55], v[58:59]
	s_nop 0
	v_cvt_pk_bf16_f32 v54, v58, v59
	v_cvt_pk_bf16_f32 v55, v60, v61
	global_store_dwordx2 v[72:73], v[54:55], off offset:256
	v_mul_f32_e32 v59, v59, v59
	v_mul_f32_e32 v61, v61, v61
	v_fmac_f32_e32 v59, v58, v58
	v_fmac_f32_e32 v61, v60, v60
	v_add_f32_e32 v58, v59, v61
	v_add_f32_e32 v58, v62, v58
	s_waitcnt vmcnt(23)
	v_mov_b32_e32 v54, v228
	v_mov_b32_e32 v55, v229
	v_mov_b32_e32 v56, v230
	v_mov_b32_e32 v57, v231
	s_mov_b32 s76, 0xb0000
	v_lshl_add_u64 v[250:251], v[252:253], 0, s[76:77]
	global_load_dwordx4 v[216:219], v[250:251], off nt
	global_load_dwordx4 v[220:223], v[250:251], off offset:64 nt
	global_load_dwordx4 v[224:227], v[250:251], off offset:512 nt
	global_load_dwordx4 v[228:231], v[250:251], off offset:576 nt
	v_pk_add_f32 v[52:53], v[52:53], v[56:57]
	v_pk_add_f32 v[54:55], v[50:51], v[54:55]
	v_mul_f32_e32 v51, v53, v53
	v_mul_f32_e32 v50, v55, v55
	v_fmac_f32_e32 v50, v54, v54
	v_fmac_f32_e32 v51, v52, v52
	v_add_f32_e32 v50, v50, v51
	v_add_f32_e32 v50, v58, v50
	ds_bpermute_b32 v51, v122, v50
	v_cvt_pk_bf16_f32 v54, v54, v55
	v_cvt_pk_bf16_f32 v55, v52, v53
	global_store_dwordx2 v[72:73], v[54:55], off offset:288
	s_waitcnt lgkmcnt(0)
	v_add_f32_e32 v50, v50, v51
	ds_bpermute_b32 v51, v120, v50
	s_and_saveexec_b64 s[62:63], s[4:5]
	s_cbranch_execz .LBB0_783
	s_waitcnt lgkmcnt(0)
	v_add_f32_e32 v52, v50, v51
	v_lshl_add_u64 v[50:51], v[66:67], 2, s[18:19]
	global_atomic_add_f32 v[50:51], v52, off
